# LRU items: top-of-item vmcnt wait no longer waits for the previous item's output stores (pass C: vmcnt(2); pass A: prefetch drained at the pre-aggregate barrier, vmcnt(1) at the top)
# speedup vs baseline: 1.0071x; 1.0016x over previous
; template <bool PASS_C>
; DEVI void lru_item(const P& p, int item, int next_item, uint4& u0, uint4& u1, uint4& u2, float& cpre, char* smem) {
;     ...
;     __syncthreads();
;     *(uint4*)(us + tid * 8) = u0;
;     *(uint4*)(us + (tid + 256) * 8) = u1;
;     if (tid < 24) *(uint4*)(us + (tid + 512) * 8) = u2;
;     if (PASS_C && tid < 128) carry[tid] = cpre;
;     uint4 sg0 = {0u, 0u, 0u, 0u}, sg1 = {0u, 0u, 0u, 0u};
;     if (PASS_C) {
;         const bf16_t* SG = (const bf16_t*)(p.ws + OFF_C) + (rbase + tb + (tid >> 2)) * 1024 + h * 64 + (tid & 3) * 16;
;         sg0 = *(const uint4*)(SG); sg1 = *(const uint4*)(SG + 8);
;     }
;     if (next_item >= 0) {
;         lru_load_us(p, next_item, tid, u0, u1, u2);
.LBB0_500:
	s_waitcnt vmcnt(1) lgkmcnt(0)
	s_barrier
	ds_write_b128 v140, v[4:7] offset:35840
	ds_write_b128 v140, v[0:3] offset:39936
	s_and_saveexec_b64 s[12:13], s[6:7]
	ds_write_b128 v140, v[8:11] offset:44032
	s_or_b64 exec, exec, s[12:13]
	s_add_i32 s36, s34, s27
	s_cmpk_gt_i32 s36, 0x21ff
	s_cselect_b64 s[14:15], -1, 0
	s_cmpk_lt_i32 s36, 0x2200
	s_cselect_b32 s12, s36, -1
	s_cmp_lt_i32 s12, 0
	s_cbranch_scc1 .LBB0_510
	s_lshr_b32 s0, s12, 4
	s_mul_hi_u32 s13, s0, 0x3c3c3c4
	s_mulk_i32 s13, 0x44
	s_sub_i32 s17, s0, s13
	s_mul_hi_u32 s0, s12, 0xf0f0f0f1
	s_lshr_b32 s13, s0, 10
	s_cmp_lt_u32 s17, 4
	s_mul_hi_u32 s18, s13, 0x880000
	s_mul_i32 s13, s13, 0x880000
	s_cselect_b32 s0, 0, 0x100
	s_cselect_b32 s16, 0x100, s31
	s_add_u32 s13, s80, s13
	s_addc_u32 s18, s81, s18
	s_lshl_b32 s12, s12, 7
	s_and_b32 s12, s12, 0x780
	s_add_u32 s12, s13, s12
	s_addc_u32 s13, s18, 0
	v_mov_b32_e32 v89, v69
	v_lshl_add_u32 v8, s17, 6, v110
	v_mov_b32_e32 v2, v69
	v_mov_b32_e32 v3, v69
	v_lshl_add_u64 v[12:13], s[12:13], 0, v[88:89]
	v_cmp_le_i32_e32 vcc, s0, v8
	v_cmp_gt_i32_e64 s[12:13], s16, v8
	v_mov_b32_e32 v0, 0
	v_mov_b32_e32 v1, v69
	v_mov_b64_e32 v[6:7], v[2:3]
	s_and_b64 s[18:19], vcc, s[12:13]
	v_mov_b64_e32 v[4:5], v[0:1]
	s_and_saveexec_b64 s[12:13], s[18:19]
	s_cbranch_execz .LBB0_505
	v_mov_b32_e32 v9, v69
	v_lshlrev_b64 v[4:5], 11, v[8:9]
	v_lshl_add_u64 v[4:5], v[12:13], 0, v[4:5]
	global_load_dwordx4 v[4:7], v[4:5], off

; template <bool PASS_C>
; DEVI void lru_item(const P& p, int item, int next_item, uint4& u0, uint4& u1, uint4& u2, float& cpre, char* smem) {
;     ...
;     __syncthreads();
;     if (!PASS_C) {
;         if (tid < 128) {
;             const int d = tid >> 6, ch = tid & 63;
;             float A = 1.f, Bq = 0.f;
;             if (d == 0) {
; #pragma unroll
;                 for (int ww = 0; ww < 4; ++ww) { const float a_ = wagg[((ww * 2 + d) * 64 + ch) * 2], b_ = wagg[((ww * 2 + d) * 64 + ch) * 2 + 1]; Bq = a_ * Bq + b_; A *= a_; }
;             } else {
; #pragma unroll
;     ...
;             }
;             agg[(size_t)(b * NCH + c) * 2048 + d * 1024 + h * 64 + ch] = make_float2(A, Bq);
.LBB0_526:
	s_or_b64 exec, exec, s[12:13]
	s_waitcnt vmcnt(0) lgkmcnt(0)
	s_barrier
	s_and_saveexec_b64 s[12:13], s[10:11]
	s_cbranch_execz .LBB0_495
	v_add_u32_e32 v14, 0, v100
	s_and_saveexec_b64 s[16:17], s[4:5]
	s_xor_b64 s[20:21], exec, s[16:17]
	s_cbranch_execz .LBB0_529
	ds_read2st64_b64 v[16:19], v14 offset0:107 offset1:109
	ds_read2st64_b64 v[20:23], v14 offset0:103 offset1:105
	s_waitcnt lgkmcnt(1)
	v_fma_f32 v13, 0, v18, v19
	v_fmac_f32_e32 v17, v13, v16
	v_mul_f32_e32 v12, v18, v16
	s_waitcnt lgkmcnt(0)
	v_fma_f32 v13, v17, v22, v23
	v_mov_b32_e32 v23, v20
	v_pk_mul_f32 v[14:15], v[12:13], v[22:23]
	v_pk_fma_f32 v[12:13], v[12:13], v[22:23], v[20:21]
	s_nop 0
	v_mul_f32_e32 v12, v14, v20

; template <bool PASS_C>
; DEVI void lru_item(const P& p, int item, int next_item, uint4& u0, uint4& u1, uint4& u2, float& cpre, char* smem) {
;     ...
;     __syncthreads();
;     *(uint4*)(us + tid * 8) = u0;
;     *(uint4*)(us + (tid + 256) * 8) = u1;
;     if (tid < 24) *(uint4*)(us + (tid + 512) * 8) = u2;
;     if (PASS_C && tid < 128) carry[tid] = cpre;
;     uint4 sg0 = {0u, 0u, 0u, 0u}, sg1 = {0u, 0u, 0u, 0u};
;     if (PASS_C) {
;         const bf16_t* SG = (const bf16_t*)(p.ws + OFF_C) + (rbase + tb + (tid >> 2)) * 1024 + h * 64 + (tid & 3) * 16;
;         sg0 = *(const uint4*)(SG); sg1 = *(const uint4*)(SG + 8);
;     }
;     if (next_item >= 0) {
;         lru_load_us(p, next_item, tid, u0, u1, u2);
;         if (PASS_C && tid < 128) {
;             const int nh = next_item & 15, nc = (next_item >> 4) % NCH, nb = next_item / (16 * NCH);
;             cpre = ((const float*)(p.ws + OFF_CIN))[(size_t)(nb * NCH + nc) * 2048 + (tid >> 6) * 1024 + nh * 64 + (tid & 63)];
;         }
.LBB0_725:
	s_barrier
	s_waitcnt vmcnt(2)
	ds_write_b128 v115, v[4:7] offset:35840
	ds_write_b128 v115, v[0:3] offset:39936
	s_and_saveexec_b64 s[28:29], s[6:7]
	ds_write_b128 v115, v[10:13] offset:44032
	s_or_b64 exec, exec, s[28:29]
	s_and_saveexec_b64 s[28:29], s[8:9]
	ds_write_b32 v126, v8 offset:56832
	s_or_b64 exec, exec, s[28:29]
	s_add_i32 s59, s33, s27
	s_cmpk_gt_i32 s59, 0x21ff
	s_cselect_b64 s[30:31], -1, 0
	s_cmpk_lt_i32 s59, 0x2200
	s_cselect_b32 s28, s59, -1
	s_ashr_i32 s0, s33, 4
	s_mul_hi_i32 s26, s0, 0x78787879
	s_lshr_b32 s29, s26, 31
	s_lshr_b32 s26, s26, 5
	s_add_i32 s26, s26, s29
	s_mulk_i32 s26, 0x44
	s_sub_i32 s0, s0, s26
	s_mul_hi_i32 s26, s33, 0x78787879
	s_lshr_b32 s29, s26, 31
	s_ashr_i32 s26, s26, 9
	s_add_i32 s26, s26, s29
	s_lshl_b32 s44, s0, 6
	s_mul_hi_i32 s0, s26, 0x1100
	s_mulk_i32 s26, 0x1100
	s_ashr_i32 s45, s44, 31
	v_mov_b32_e32 v15, s0
	v_or_b32_e32 v14, s26, v82
	v_lshl_add_u64 v[22:23], v[14:15], 0, s[44:45]
	v_lshlrev_b64 v[14:15], 11, v[22:23]
	s_and_b32 s0, s34, 0x3c0
	v_lshl_add_u64 v[14:15], s[82:83], 0, v[14:15]
	s_lshl_b32 s0, s0, 1
	v_lshl_add_u64 v[14:15], v[14:15], 0, s[0:1]
	v_lshl_add_u64 v[18:19], v[14:15], 0, v[78:79]
	global_load_dwordx4 v[14:17], v[18:19], off offset:16
	s_nop 0
	global_load_dwordx4 v[18:21], v[18:19], off
	s_cmp_lt_i32 s28, 0
	s_cbranch_scc1 .LBB0_739
	s_lshr_b32 s26, s28, 4
	s_mul_hi_u32 s29, s26, 0x3c3c3c4
	s_mulk_i32 s29, 0x44
	s_sub_i32 s26, s26, s29
	s_mul_hi_u32 s29, s28, 0xf0f0f0f1
	s_lshr_b32 s33, s29, 10
	s_cmp_lt_u32 s26, 4
	s_mul_i32 s44, s33, 0x880000
	s_cselect_b32 s45, 0, 0x100
	s_cselect_b32 s60, s51, 0x1100
	s_mul_hi_u32 s29, s33, 0x880000
	s_add_u32 s61, s80, s44
	s_addc_u32 s29, s81, s29
	s_lshl_b32 s28, s28, 6
	s_and_b32 s44, s28, 0x3c0
	s_lshl_b32 s28, s44, 1
	s_add_u32 s28, s61, s28
	s_addc_u32 s29, s29, 0
	v_mov_b32_e32 v103, v79
	v_lshl_add_u32 v10, s26, 6, v116
	v_mov_b32_e32 v2, v79
	v_mov_b32_e32 v3, v79
	v_lshl_add_u64 v[24:25], s[28:29], 0, v[102:103]
	v_cmp_le_i32_e32 vcc, s45, v10
	v_cmp_gt_i32_e64 s[28:29], s60, v10
	v_mov_b32_e32 v0, 0
	v_mov_b32_e32 v1, v79
	v_mov_b64_e32 v[6:7], v[2:3]
	s_and_b64 s[62:63], vcc, s[28:29]
	v_mov_b64_e32 v[4:5], v[0:1]
	s_and_saveexec_b64 s[28:29], s[62:63]
	s_cbranch_execz .LBB0_732
	v_mov_b32_e32 v11, v79
	v_lshlrev_b64 v[4:5], 11, v[10:11]
	v_lshl_add_u64 v[4:5], v[24:25], 0, v[4:5]
	global_load_dwordx4 v[4:7], v[4:5], off

; template <bool PASS_C>
; DEVI void lru_item(const P& p, int item, int next_item, uint4& u0, uint4& u1, uint4& u2, float& cpre, char* smem) {
;     ...
;     __syncthreads();
;     *(uint4*)(us + tid * 8) = u0;
;     *(uint4*)(us + (tid + 256) * 8) = u1;
;     if (tid < 24) *(uint4*)(us + (tid + 512) * 8) = u2;
;     if (PASS_C && tid < 128) carry[tid] = cpre;
;     uint4 sg0 = {0u, 0u, 0u, 0u}, sg1 = {0u, 0u, 0u, 0u};
;     if (PASS_C) {
;         const bf16_t* SG = (const bf16_t*)(p.ws + OFF_C) + (rbase + tb + (tid >> 2)) * 1024 + h * 64 + (tid & 3) * 16;
;         sg0 = *(const uint4*)(SG); sg1 = *(const uint4*)(SG + 8);
;     }
;     if (next_item >= 0) {
;         lru_load_us(p, next_item, tid, u0, u1, u2);
;         if (PASS_C && tid < 128) {
;             const int nh = next_item & 15, nc = (next_item >> 4) % NCH, nb = next_item / (16 * NCH);
;             cpre = ((const float*)(p.ws + OFF_CIN))[(size_t)(nb * NCH + nc) * 2048 + (tid >> 6) * 1024 + nh * 64 + (tid & 63)];
;         }
.LBB0_1048:
	s_waitcnt lgkmcnt(0)
	s_barrier
	s_waitcnt vmcnt(2)
	ds_write_b128 v115, v[4:7] offset:35840
	ds_write_b128 v115, v[0:3] offset:39936
	s_and_saveexec_b64 s[28:29], s[6:7]
	ds_write_b128 v115, v[10:13] offset:44032
	s_or_b64 exec, exec, s[28:29]
	s_and_saveexec_b64 s[28:29], s[8:9]
	ds_write_b32 v126, v8 offset:56832
	s_or_b64 exec, exec, s[28:29]
	s_add_i32 s51, s33, s27
	s_cmpk_gt_i32 s51, 0x21ff
	s_cselect_b64 s[30:31], -1, 0
	s_cmpk_lt_i32 s51, 0x2200
	s_cselect_b32 s28, s51, -1
	s_ashr_i32 s0, s33, 4
	s_mul_hi_i32 s26, s0, 0x78787879
	s_lshr_b32 s29, s26, 31
	s_lshr_b32 s26, s26, 5
	s_add_i32 s26, s26, s29
	s_mulk_i32 s26, 0x44
	s_sub_i32 s0, s0, s26
	s_mul_hi_i32 s26, s33, 0x78787879
	s_lshr_b32 s29, s26, 31
	s_ashr_i32 s26, s26, 9
	s_add_i32 s26, s26, s29
	s_lshl_b32 s44, s0, 6
	s_mul_hi_i32 s0, s26, 0x1100
	s_mulk_i32 s26, 0x1100
	s_ashr_i32 s45, s44, 31
	v_mov_b32_e32 v15, s0
	v_or_b32_e32 v14, s26, v82
	v_lshl_add_u64 v[22:23], v[14:15], 0, s[44:45]
	v_lshlrev_b64 v[14:15], 11, v[22:23]
	s_and_b32 s0, s34, 0x3c0
	v_lshl_add_u64 v[14:15], s[82:83], 0, v[14:15]
	s_lshl_b32 s0, s0, 1
	v_lshl_add_u64 v[14:15], v[14:15], 0, s[0:1]
	v_lshl_add_u64 v[18:19], v[14:15], 0, v[78:79]
	global_load_dwordx4 v[14:17], v[18:19], off offset:16
	s_nop 0
	global_load_dwordx4 v[18:21], v[18:19], off
	s_cmp_lt_i32 s28, 0
	s_cbranch_scc1 .LBB0_1062
	s_lshr_b32 s26, s28, 4
	s_mul_hi_u32 s29, s26, 0x3c3c3c4
	s_mulk_i32 s29, 0x44
	s_sub_i32 s26, s26, s29
	s_mul_hi_u32 s29, s28, 0xf0f0f0f1
	s_lshr_b32 s33, s29, 10
	s_cmp_lt_u32 s26, 4
	s_mul_i32 s44, s33, 0x880000
	s_cselect_b32 s45, 0, 0x100
	s_cselect_b32 s58, s43, 0x1100
	s_mul_hi_u32 s29, s33, 0x880000
	s_add_u32 s59, s80, s44
	s_addc_u32 s29, s81, s29
	s_lshl_b32 s28, s28, 6
	s_and_b32 s44, s28, 0x3c0
	s_lshl_b32 s28, s44, 1
	s_add_u32 s28, s59, s28
	s_addc_u32 s29, s29, 0
	v_mov_b32_e32 v103, v79
	v_lshl_add_u32 v10, s26, 6, v116
	v_mov_b32_e32 v2, v79
	v_mov_b32_e32 v3, v79
	v_lshl_add_u64 v[24:25], s[28:29], 0, v[102:103]
	v_cmp_le_i32_e32 vcc, s45, v10
	v_cmp_gt_i32_e64 s[28:29], s58, v10
	v_mov_b32_e32 v0, 0
	v_mov_b32_e32 v1, v79
	v_mov_b64_e32 v[6:7], v[2:3]
	s_and_b64 s[60:61], vcc, s[28:29]
	v_mov_b64_e32 v[4:5], v[0:1]
	s_and_saveexec_b64 s[28:29], s[60:61]
	s_cbranch_execz .LBB0_1055
	v_mov_b32_e32 v11, v79
	v_lshlrev_b64 v[4:5], 11, v[10:11]
	v_lshl_add_u64 v[4:5], v[24:25], 0, v[4:5]
	global_load_dwordx4 v[4:7], v[4:5], off
